# W2 transposes for FFN instance 0 moved from prologue to the 40 CUs idle in the last FFN0-up round (VGPRs saved/restored through LDS)
# speedup vs baseline: 1.0554x; 1.0004x over previous
; __device__ __forceinline__ void prologue(const Params& p, LAS unsigned char* lds) {
;     ...
;         for (int it = gw; it < NITEMS; it += NGW) {
;             int r = it;
;             if (r < 4 * I_W1) { const int mi = r / I_W1; r -= mi * I_W1; const int kb = r / 176, nb = r % 176;
;                 transpose_item(p.in[I_FFNWIN] + (size_t)mi * D * NFF1, D, NFF1, (bf16_t*)(ws + WS_W1T + mi * SZ_W1T), paired_src(nb * 32, DFF), nb * 32, kb * 64, scr, lane); continue; }
;             r -= 4 * I_W1;
;             if (r < 4 * I_W2) { const int mi = r / I_W2; r -= mi * I_W2; const int kb = r / 32, nb = r % 32;
;                 transpose_item(p.in[I_FFNWOUT] + (size_t)mi * DFF * D, DFF, D, (bf16_t*)(ws + WS_W2T + mi * SZ_W2T), nb * 32, nb * 32, kb * 64, scr, lane); continue; }
;             r -= 4 * I_W2;
;             if (r < I_AB) { const int kb = r / 80, nb = r % 80; const int nd = nb * 32, nsrc = nd < 1024 ? paired_src(nd, 512) : nd;
;                 transpose_item(p.in[I_ABWIN], D, NAB, (bf16_t*)(ws + WS_WABT), nsrc, nd, kb * 64, scr, lane); continue; }
;             r -= I_AB;
;             if (r < I_SQ) { const int kb = r / 32, nb = r % 32; transpose_item(p.in[I_ABWOUT], D, D, (bf16_t*)(ws + WS_WOT), nb * 32, nb * 32, kb * 64, scr, lane); continue; }
;             r -= I_SQ;
;             { const int kb = r / 32, nb = r % 32; transpose_item(p.in[I_FNETW], D, D, (bf16_t*)(ws + WS_WFT), nb * 32, nb * 32, kb * 64, scr, lane); }
;         }
.LBB0_30:
	s_or_b64 exec, exec, s[8:9]
	v_add_u32_e32 v39, s94, v39
	v_add_u32_e32 v28, s18, v28
	v_add_u32_e32 v29, s19, v29
	v_mov_b32_e32 v255, 0x20ff
	v_cmp_lt_u32_e32 vcc, v255, v39
	v_mov_b32_e32 v255, 0x4200
	v_cmp_gt_u32_e64 s[98:99], v255, v39
	s_and_b64 vcc, vcc, s[98:99]
	s_cmpk_eq_u32 s82, 0x100
	s_cselect_b64 s[98:99], -1, 0
	s_and_b64 vcc, vcc, s[98:99]
	v_cndmask_b32_e64 v255, 0, 1, vcc
	v_mul_u32_u24_e32 v254, 0x2100, v255
	v_add_u32_e32 v39, v39, v254
	v_mul_u32_u24_e32 v254, 0x42000, v255
	v_add_u32_e32 v28, v28, v254
	v_mul_u32_u24_e32 v254, 0x4200, v255
	v_add_u32_e32 v29, v29, v254
	v_cmp_lt_i32_e32 vcc, s40, v39
	s_or_b64 s[6:7], vcc, s[6:7]
	s_andn2_b64 exec, exec, s[6:7]
	s_cbranch_execz .LBB0_49

; #define LAS __attribute__((address_space(3)))
; __device__ __forceinline__ void transpose_item(const float* W, int K, int N, bf16_t* WT, int n0src, int n0dst, int k0, LAS float* scr, int lane) {
;     float v[32];
; #pragma unroll
;     for (int i = 0; i < 32; ++i) { const int kk = 2 * i + (lane >> 5); v[i] = W[(size_t)(k0 + kk) * N + n0src + (lane & 31)]; }
; #pragma unroll
;     for (int i = 0; i < 32; ++i) { const int kk = 2 * i + (lane >> 5); scr[kk * 33 + (lane & 31)] = v[i]; }
;     asm volatile("s_waitcnt lgkmcnt(0)" ::: "memory");
; __device__ __forceinline__ void prologue(const Params& p, LAS unsigned char* lds) {
;     ...
;             if (r < 4 * I_W2) { const int mi = r / I_W2; r -= mi * I_W2; const int kb = r / 32, nb = r % 32;
;                 transpose_item(p.in[I_FFNWOUT] + (size_t)mi * DFF * D, DFF, D, (bf16_t*)(ws + WS_W2T + mi * SZ_W2T), nb * 32, nb * 32, kb * 64, scr, lane); continue; }
.LBB0_235:
	s_waitcnt vmcnt(0)
	s_barrier
	s_cmpk_lg_u32 s82, 0x100
	s_cbranch_scc1 .Ltr_done_q
	s_cmpk_lt_u32 s84, 0xd8
	s_cbranch_scc1 .Ltr_done_q
	s_mov_b64 s[48:49], exec
	s_mov_b64 exec, -1
	v_readfirstlane_b32 s99, v176
	s_lshr_b32 s99, s99, 6
	s_sub_i32 s43, s84, 0xd8
	s_lshl_b32 s42, s43, 3
	s_add_i32 s42, s42, s99
	s_lshl_b32 s99, s99, 14
	v_and_b32_e32 v231, 63, v176
	v_and_b32_e32 v232, 31, v231
	v_lshrrev_b32_e32 v233, 5, v231
	v_mul_u32_u24_e32 v234, 0x84, v233
	v_lshl_add_u32 v234, v232, 2, v234
	v_add_u32_e32 v234, s99, v234
	v_and_b32_e32 v235, 7, v231
	v_lshrrev_b32_e32 v236, 3, v231
	v_mul_u32_u24_e32 v237, 0x420, v235
	v_lshl_add_u32 v237, v236, 2, v237
	v_add_u32_e32 v237, s99, v237
	v_lshlrev_b32_e32 v255, 2, v231
	v_add_u32_e32 v255, s99, v255
	v_add_u32_e32 v255, 0x2100, v255
	ds_write_b32 v255, v40
	ds_write_b32 v255, v41 offset:256
	ds_write_b32 v255, v42 offset:512
	ds_write_b32 v255, v43 offset:768
	ds_write_b32 v255, v44 offset:1024
	ds_write_b32 v255, v45 offset:1280
	ds_write_b32 v255, v46 offset:1536
	ds_write_b32 v255, v47 offset:1792
	ds_write_b32 v255, v48 offset:2048
	ds_write_b32 v255, v49 offset:2304
	ds_write_b32 v255, v50 offset:2560
	ds_write_b32 v255, v51 offset:2816
	ds_write_b32 v255, v52 offset:3072
	ds_write_b32 v255, v53 offset:3328
	ds_write_b32 v255, v54 offset:3584
	ds_write_b32 v255, v55 offset:3840
	ds_write_b32 v255, v56 offset:4096
	ds_write_b32 v255, v57 offset:4352
	ds_write_b32 v255, v58 offset:4608
	ds_write_b32 v255, v59 offset:4864
	v_lshlrev_b32_e32 v238, 12, v233
	v_lshl_add_u32 v238, v232, 2, v238
	v_mul_u32_u24_e32 v239, 0x1600, v236
	v_lshl_add_u32 v239, v235, 4, v239
	v_readlane_b32 s44, v253, 0
	v_readlane_b32 s45, v253, 1
	s_add_u32 s46, s80, 0x2e00000
	s_addc_u32 s47, s81, 0
	s_mov_b32 s98, s42
	s_cmpk_ge_u32 s98, 0x580
	s_cbranch_scc1 .Ltr_end_q0
.Ltr_loop_q0:
	s_lshr_b32 s100, s98, 5
	s_and_b32 s101, s98, 31
	s_lshl_b32 s0, s100, 18
	s_lshl_b32 s1, s101, 7
	s_add_u32 s0, s0, s1
	s_add_u32 s0, s44, s0
	s_addc_u32 s1, s45, 0
	global_load_dword v40, v238, s[0:1] nt
	s_add_u32 s0, s0, 0x2000
	s_addc_u32 s1, s1, 0
	global_load_dword v41, v238, s[0:1] nt
	s_add_u32 s0, s0, 0x2000
	s_addc_u32 s1, s1, 0
	global_load_dword v42, v238, s[0:1] nt
	s_add_u32 s0, s0, 0x2000
	s_addc_u32 s1, s1, 0
	global_load_dword v43, v238, s[0:1] nt
	s_add_u32 s0, s0, 0x2000
	s_addc_u32 s1, s1, 0
	global_load_dword v44, v238, s[0:1] nt
	s_add_u32 s0, s0, 0x2000
	s_addc_u32 s1, s1, 0
	global_load_dword v45, v238, s[0:1] nt
	s_add_u32 s0, s0, 0x2000
	s_addc_u32 s1, s1, 0
	global_load_dword v46, v238, s[0:1] nt
	s_add_u32 s0, s0, 0x2000
	s_addc_u32 s1, s1, 0
	global_load_dword v47, v238, s[0:1] nt
	s_add_u32 s0, s0, 0x2000
	s_addc_u32 s1, s1, 0
	global_load_dword v48, v238, s[0:1] nt
	s_add_u32 s0, s0, 0x2000
	s_addc_u32 s1, s1, 0
	global_load_dword v49, v238, s[0:1] nt
	s_add_u32 s0, s0, 0x2000
	s_addc_u32 s1, s1, 0
	global_load_dword v50, v238, s[0:1] nt
	s_add_u32 s0, s0, 0x2000
	s_addc_u32 s1, s1, 0
	global_load_dword v51, v238, s[0:1] nt
	s_add_u32 s0, s0, 0x2000
	s_addc_u32 s1, s1, 0
	global_load_dword v52, v238, s[0:1] nt
	s_add_u32 s0, s0, 0x2000
	s_addc_u32 s1, s1, 0
	global_load_dword v53, v238, s[0:1] nt
	s_add_u32 s0, s0, 0x2000
	s_addc_u32 s1, s1, 0
	global_load_dword v54, v238, s[0:1] nt
	s_add_u32 s0, s0, 0x2000
	s_addc_u32 s1, s1, 0
	global_load_dword v55, v238, s[0:1] nt
	s_add_u32 s0, s0, 0x2000
	s_addc_u32 s1, s1, 0
	global_load_dword v56, v238, s[0:1] nt
	s_add_u32 s0, s0, 0x2000
	s_addc_u32 s1, s1, 0
	global_load_dword v57, v238, s[0:1] nt
	s_add_u32 s0, s0, 0x2000
	s_addc_u32 s1, s1, 0
	global_load_dword v58, v238, s[0:1] nt
	s_add_u32 s0, s0, 0x2000
	s_addc_u32 s1, s1, 0
	global_load_dword v59, v238, s[0:1] nt
	s_add_u32 s0, s0, 0x2000
	s_addc_u32 s1, s1, 0
	global_load_dword v240, v238, s[0:1] nt
	s_add_u32 s0, s0, 0x2000
	s_addc_u32 s1, s1, 0
	global_load_dword v241, v238, s[0:1] nt
	s_add_u32 s0, s0, 0x2000
	s_addc_u32 s1, s1, 0
	global_load_dword v242, v238, s[0:1] nt
	s_add_u32 s0, s0, 0x2000
	s_addc_u32 s1, s1, 0
	global_load_dword v243, v238, s[0:1] nt
	s_add_u32 s0, s0, 0x2000
	s_addc_u32 s1, s1, 0
	global_load_dword v244, v238, s[0:1] nt
	s_add_u32 s0, s0, 0x2000
	s_addc_u32 s1, s1, 0
	global_load_dword v245, v238, s[0:1] nt
	s_add_u32 s0, s0, 0x2000
	s_addc_u32 s1, s1, 0
	global_load_dword v246, v238, s[0:1] nt
	s_add_u32 s0, s0, 0x2000
	s_addc_u32 s1, s1, 0
	global_load_dword v247, v238, s[0:1] nt
	s_add_u32 s0, s0, 0x2000
	s_addc_u32 s1, s1, 0
	global_load_dword v248, v238, s[0:1] nt
	s_add_u32 s0, s0, 0x2000
	s_addc_u32 s1, s1, 0
	global_load_dword v249, v238, s[0:1] nt
	s_add_u32 s0, s0, 0x2000
	s_addc_u32 s1, s1, 0
	global_load_dword v250, v238, s[0:1] nt
	s_add_u32 s0, s0, 0x2000
	s_addc_u32 s1, s1, 0
	global_load_dword v251, v238, s[0:1] nt
	s_waitcnt vmcnt(31)
	ds_write_b32 v234, v40
	s_waitcnt vmcnt(30)
	ds_write_b32 v234, v41 offset:264
	s_waitcnt vmcnt(29)
	ds_write_b32 v234, v42 offset:528
	s_waitcnt vmcnt(28)
	ds_write_b32 v234, v43 offset:792
	s_waitcnt vmcnt(27)
	ds_write_b32 v234, v44 offset:1056
	s_waitcnt vmcnt(26)
	ds_write_b32 v234, v45 offset:1320
	s_waitcnt vmcnt(25)
	ds_write_b32 v234, v46 offset:1584
	s_waitcnt vmcnt(24)
	ds_write_b32 v234, v47 offset:1848
	s_waitcnt vmcnt(23)
	ds_write_b32 v234, v48 offset:2112
	s_waitcnt vmcnt(22)
	ds_write_b32 v234, v49 offset:2376
	s_waitcnt vmcnt(21)
	ds_write_b32 v234, v50 offset:2640
	s_waitcnt vmcnt(20)
	ds_write_b32 v234, v51 offset:2904
	s_waitcnt vmcnt(19)
	ds_write_b32 v234, v52 offset:3168
	s_waitcnt vmcnt(18)
; #define LAS __attribute__((address_space(3)))
; __device__ __forceinline__ unsigned cvt_pk_bf16(float lo, float hi) { unsigned r; asm volatile("v_cvt_pk_bf16_f32 %0, %1, %2" : "=v"(r) : "v"(lo), "v"(hi)); return r; }
; #define ST16(grp, p, v) do { if ((NTG >> (grp)) & 1) NT16(p, v); else PL16(p, v); } while (0)
; __device__ __forceinline__ void xcd_barrier(const XcdBarrier& b) {
;     asm volatile("s_waitcnt vmcnt(0)" ::: "memory");
;     __syncthreads();
;     if (threadIdx.x == 0) {
;         unsigned* bar = b.bar;
;         __builtin_amdgcn_s_waitcnt(0);
;         unsigned nloc = b.st[0], nx = b.st[1];
;         if (nloc == 0u) { xcd_barrier_complete(bar, b.x, nloc, nx); b.st[0] = nloc; b.st[1] = nx; }
; __device__ __forceinline__ void transpose_item(const float* W, int K, int N, bf16_t* WT, int n0src, int n0dst, int k0, LAS float* scr, int lane) {
;     ...
;     asm volatile("s_waitcnt lgkmcnt(0)" ::: "memory");
;     const int c = lane & 7;
; #pragma unroll
;     for (int j = 0; j < 4; ++j) { const int n = (lane >> 3) + 8 * j; const LAS float* s = scr + (8 * c) * 33 + n;
;         u32x4 o; o.x = cvt_pk_bf16(s[0 * 33], s[1 * 33]); o.y = cvt_pk_bf16(s[2 * 33], s[3 * 33]); o.z = cvt_pk_bf16(s[4 * 33], s[5 * 33]); o.w = cvt_pk_bf16(s[6 * 33], s[7 * 33]);
;         ST16(6, WT + (size_t)(n0dst + n) * K + k0 + 8 * c, o); }
;     asm volatile("s_waitcnt lgkmcnt(0)" ::: "memory");
; }
	ds_write_b32 v234, v53 offset:3432
	s_waitcnt vmcnt(17)
	ds_write_b32 v234, v54 offset:3696
	s_waitcnt vmcnt(16)
	ds_write_b32 v234, v55 offset:3960
	s_waitcnt vmcnt(15)
	ds_write_b32 v234, v56 offset:4224
	s_waitcnt vmcnt(14)
	ds_write_b32 v234, v57 offset:4488
	s_waitcnt vmcnt(13)
	ds_write_b32 v234, v58 offset:4752
	s_waitcnt vmcnt(12)
	ds_write_b32 v234, v59 offset:5016
	s_waitcnt vmcnt(11)
	ds_write_b32 v234, v240 offset:5280
	s_waitcnt vmcnt(10)
	ds_write_b32 v234, v241 offset:5544
	s_waitcnt vmcnt(9)
	ds_write_b32 v234, v242 offset:5808
	s_waitcnt vmcnt(8)
	ds_write_b32 v234, v243 offset:6072
	s_waitcnt vmcnt(7)
	ds_write_b32 v234, v244 offset:6336
	s_waitcnt vmcnt(6)
	ds_write_b32 v234, v245 offset:6600
	s_waitcnt vmcnt(5)
	ds_write_b32 v234, v246 offset:6864
	s_waitcnt vmcnt(4)
	ds_write_b32 v234, v247 offset:7128
	s_waitcnt vmcnt(3)
	ds_write_b32 v234, v248 offset:7392
	s_waitcnt vmcnt(2)
	ds_write_b32 v234, v249 offset:7656
	s_waitcnt vmcnt(1)
	ds_write_b32 v234, v250 offset:7920
	s_waitcnt vmcnt(0)
	ds_write_b32 v234, v251 offset:8184
	s_mul_i32 s0, s101, 0x2c000
	s_lshl_b32 s1, s100, 7
	s_add_u32 s0, s0, s1
	s_add_u32 s0, s46, s0
	s_addc_u32 s1, s47, 0
	s_waitcnt lgkmcnt(0)
	ds_read_b32 v40, v237
	ds_read_b32 v41, v237 offset:132
	ds_read_b32 v42, v237 offset:264
	ds_read_b32 v43, v237 offset:396
	ds_read_b32 v44, v237 offset:528
	ds_read_b32 v45, v237 offset:660
	ds_read_b32 v46, v237 offset:792
	ds_read_b32 v47, v237 offset:924
	ds_read_b32 v48, v237 offset:32
	ds_read_b32 v49, v237 offset:164
	ds_read_b32 v50, v237 offset:296
	ds_read_b32 v51, v237 offset:428
	ds_read_b32 v52, v237 offset:560
	ds_read_b32 v53, v237 offset:692
	ds_read_b32 v54, v237 offset:824
	ds_read_b32 v55, v237 offset:956
	ds_read_b32 v56, v237 offset:64
	ds_read_b32 v57, v237 offset:196
	ds_read_b32 v58, v237 offset:328
	ds_read_b32 v59, v237 offset:460
	ds_read_b32 v240, v237 offset:592
	ds_read_b32 v241, v237 offset:724
	ds_read_b32 v242, v237 offset:856
	ds_read_b32 v243, v237 offset:988
	ds_read_b32 v244, v237 offset:96
	ds_read_b32 v245, v237 offset:228
	ds_read_b32 v246, v237 offset:360
	ds_read_b32 v247, v237 offset:492
	ds_read_b32 v248, v237 offset:624
	ds_read_b32 v249, v237 offset:756
	ds_read_b32 v250, v237 offset:888
	ds_read_b32 v251, v237 offset:1020
	s_waitcnt lgkmcnt(15)
	v_cvt_pk_bf16_f32 v32, v40, v41
	v_cvt_pk_bf16_f32 v33, v42, v43
	v_cvt_pk_bf16_f32 v34, v44, v45
	v_cvt_pk_bf16_f32 v35, v46, v47
	global_store_dwordx4 v239, v[32:35], s[0:1]
	s_add_u32 s0, s0, 0xb000
	s_addc_u32 s1, s1, 0
	s_waitcnt lgkmcnt(15)
	v_cvt_pk_bf16_f32 v36, v48, v49
	v_cvt_pk_bf16_f32 v37, v50, v51
	v_cvt_pk_bf16_f32 v38, v52, v53
	v_cvt_pk_bf16_f32 v39, v54, v55
	global_store_dwordx4 v239, v[36:39], s[0:1]
	s_add_u32 s0, s0, 0xb000
	s_addc_u32 s1, s1, 0
	s_waitcnt lgkmcnt(8)
	v_cvt_pk_bf16_f32 v32, v56, v57
	v_cvt_pk_bf16_f32 v33, v58, v59
	v_cvt_pk_bf16_f32 v34, v240, v241
	v_cvt_pk_bf16_f32 v35, v242, v243
	global_store_dwordx4 v239, v[32:35], s[0:1]
	s_add_u32 s0, s0, 0xb000
	s_addc_u32 s1, s1, 0
	s_waitcnt lgkmcnt(0)
	v_cvt_pk_bf16_f32 v36, v244, v245
	v_cvt_pk_bf16_f32 v37, v246, v247
	v_cvt_pk_bf16_f32 v38, v248, v249
	v_cvt_pk_bf16_f32 v39, v250, v251
	global_store_dwordx4 v239, v[36:39], s[0:1]
	s_add_i32 s98, s98, 0x140
	s_cmpk_lt_u32 s98, 0x580
	s_cbranch_scc1 .Ltr_loop_q0
.Ltr_end_q0:
	s_waitcnt lgkmcnt(0)
	ds_read_b32 v40, v255
	ds_read_b32 v41, v255 offset:256
	ds_read_b32 v42, v255 offset:512
	ds_read_b32 v43, v255 offset:768
	ds_read_b32 v44, v255 offset:1024
	ds_read_b32 v45, v255 offset:1280
	ds_read_b32 v46, v255 offset:1536
	ds_read_b32 v47, v255 offset:1792
	ds_read_b32 v48, v255 offset:2048
	ds_read_b32 v49, v255 offset:2304
	ds_read_b32 v50, v255 offset:2560
	ds_read_b32 v51, v255 offset:2816
	ds_read_b32 v52, v255 offset:3072
	ds_read_b32 v53, v255 offset:3328
	ds_read_b32 v54, v255 offset:3584
	ds_read_b32 v55, v255 offset:3840
	ds_read_b32 v56, v255 offset:4096
	ds_read_b32 v57, v255 offset:4352
	ds_read_b32 v58, v255 offset:4608
	ds_read_b32 v59, v255 offset:4864
	s_waitcnt lgkmcnt(0)
.Ltr_fin_q:
	s_mov_b64 exec, s[48:49]
.Ltr_done_q:
.LBB0_236:
	s_waitcnt vmcnt(0)
	s_waitcnt lgkmcnt(0)
	s_barrier
	s_and_saveexec_b64 s[0:1], s[90:91]
	s_cbranch_execz .LBB0_288
	s_add_i32 s12, 0, 0x20040
	v_mov_b32_e32 v0, s12
	s_waitcnt vmcnt(0) expcnt(0) lgkmcnt(0)
	ds_read_b32 v2, v0
	s_add_i32 s12, 0, 0x20044
	v_mov_b32_e32 v0, s12
	ds_read_b32 v0, v0
	s_waitcnt lgkmcnt(1)
	v_cmp_ne_u32_e32 vcc, 0, v2
	s_cbranch_vccnz .LBB0_252
	s_add_u32 s12, s80, 0x60200
	s_addc_u32 s13, s81, 0
	s_add_u32 s14, s80, 0x60400
	s_addc_u32 s15, s81, 0
	s_add_u32 s18, s80, 0x60500
	s_addc_u32 s19, s81, 0
	s_add_u32 s20, s80, 0x60600
	s_addc_u32 s21, s81, 0
	s_add_u32 s22, s80, 0x60700
	s_addc_u32 s23, s81, 0
	s_add_u32 s24, s80, 0x60800
	s_addc_u32 s25, s81, 0
	s_add_u32 s26, s80, 0x60900
	s_addc_u32 s27, s81, 0
	s_add_u32 s30, s80, 0x60a00
	s_addc_u32 s31, s81, 0
	s_add_u32 s34, s80, 0x60b00
	s_addc_u32 s35, s81, 0
	s_add_u32 s36, s80, 0x60c00
	s_addc_u32 s37, s81, 0
	s_add_u32 s38, s80, 0x60d00
	s_addc_u32 s39, s81, 0
	s_add_u32 s40, s80, 0x60e00
	s_addc_u32 s41, s81, 0
	s_add_u32 s42, s80, 0x60f00
	s_addc_u32 s43, s81, 0
	s_add_u32 s44, s80, 0x61000
	s_addc_u32 s45, s81, 0
	s_add_u32 s46, s80, 0x61100
	s_addc_u32 s47, s81, 0
	s_add_u32 s48, s80, 0x61200
	s_addc_u32 s49, s81, 0
	s_mul_i32 s33, s83, s88
	s_add_u32 s50, s80, 0x61300
	s_mul_i32 s33, s33, s82
	s_addc_u32 s51, s81, 0
	s_mov_b32 s58, 1
	v_mov_b32_e32 v16, 0
	s_branch .LBB0_240
